# attention: early K(t+1) fragment reads spread one per P.V gap (gaps 12-14) instead of a burst
# speedup vs baseline: 1.0076x; 1.0076x over previous
.LBB0_194:
	s_waitcnt lgkmcnt(2)
	v_mfma_f32_32x32x16_bf16 v[18:33], v[118:121], v[178:181], v[18:33]
	ds_read_b128 v[118:121], v247 offset:24576
	v_exp_f32_e32 v133, v102
	v_exp_f32_e32 v134, v103
	v_add_f32_e32 v131, v131, v133
	v_add_f32_e32 v132, v132, v134
	v_cvt_pk_bf16_f32 v184, v133, v134
	v_mfma_f32_32x32x16_bf16 v[2:17], v[114:117], v[178:181], v[2:17]
	ds_read_b128 v[114:117], v247 offset:28672
	v_exp_f32_e32 v130, v104
	v_exp_f32_e32 v133, v105
	v_add_f32_e32 v131, v131, v130
	v_add_f32_e32 v132, v132, v133
	v_cvt_pk_bf16_f32 v185, v130, v133
	s_waitcnt lgkmcnt(2)
	v_mfma_f32_32x32x16_bf16 v[34:49], v[126:129], v[186:189], v[34:49]
	ds_read_b128 v[202:205], v239 offset:32768
	v_exp_f32_e32 v126, v106
	v_exp_f32_e32 v127, v107
	v_add_f32_e32 v128, v131, v126
	v_add_f32_e32 v129, v132, v127
	v_cvt_pk_bf16_f32 v190, v126, v127
	v_mfma_f32_32x32x16_bf16 v[50:65], v[122:125], v[186:189], v[50:65]
	ds_read_b128 v[194:197], v239 offset:40960
	v_exp_f32_e32 v124, v108
	v_exp_f32_e32 v125, v109
	v_add_f32_e32 v122, v128, v124
	v_add_f32_e32 v123, v129, v125
	v_cvt_pk_bf16_f32 v191, v124, v125
.LBB0_196:
	s_waitcnt lgkmcnt(2)
	v_mfma_f32_32x32x16_bf16 v[18:33], v[118:121], v[186:189], v[18:33]
	ds_read_b128 v[198:201], v240 offset:32768
	v_exp_f32_e32 v118, v110
	v_exp_f32_e32 v119, v111
	v_add_f32_e32 v120, v122, v118
	v_add_f32_e32 v121, v123, v119
	v_cvt_pk_bf16_f32 v192, v118, v119
	v_mfma_f32_32x32x16_bf16 v[2:17], v[114:117], v[186:189], v[2:17]
	v_exp_f32_e32 v114, v112
	v_exp_f32_e32 v115, v113
	v_add_f32_e32 v116, v120, v114
	v_add_f32_e32 v117, v121, v115
	v_cvt_pk_bf16_f32 v193, v114, v115
	v_add_f32_e32 v212, v116, v117
	v_cmp_nge_f32_e32 vcc, s7, v212
	s_cbranch_vccnz .Lrare_u1e

.LBB0_234:
	s_waitcnt lgkmcnt(2)
	v_mfma_f32_32x32x16_bf16 v[18:33], v[118:121], v[182:185], v[18:33]
	ds_read_b128 v[118:121], v247 offset:40960
	v_exp_f32_e32 v135, v102
	v_exp_f32_e32 v136, v103
	v_add_f32_e32 v133, v133, v135
	v_add_f32_e32 v134, v134, v136
	v_cvt_pk_bf16_f32 v180, v135, v136
	v_mfma_f32_32x32x16_bf16 v[2:17], v[114:117], v[182:185], v[2:17]
	ds_read_b128 v[114:117], v247 offset:45056
	v_exp_f32_e32 v132, v104
	v_exp_f32_e32 v135, v105
	v_add_f32_e32 v133, v133, v132
	v_add_f32_e32 v134, v134, v135
	v_cvt_pk_bf16_f32 v181, v132, v135
	s_waitcnt lgkmcnt(2)
	v_mfma_f32_32x32x16_bf16 v[34:49], v[126:129], v[190:193], v[34:49]
	ds_read_b128 v[202:205], v239
	v_exp_f32_e32 v126, v106
	v_exp_f32_e32 v127, v107
	v_add_f32_e32 v128, v133, v126
	v_add_f32_e32 v129, v134, v127
	v_cvt_pk_bf16_f32 v186, v126, v127
	v_mfma_f32_32x32x16_bf16 v[50:65], v[122:125], v[190:193], v[50:65]
	ds_read_b128 v[194:197], v239 offset:8192
	v_exp_f32_e32 v124, v108
	v_exp_f32_e32 v125, v109
	v_add_f32_e32 v122, v128, v124
	v_add_f32_e32 v123, v129, v125
	v_cvt_pk_bf16_f32 v187, v124, v125
.LBB0_236:
	s_waitcnt lgkmcnt(2)
	v_mfma_f32_32x32x16_bf16 v[18:33], v[118:121], v[190:193], v[18:33]
	ds_read_b128 v[198:201], v240
	v_exp_f32_e32 v118, v110
	v_exp_f32_e32 v119, v111
	v_add_f32_e32 v120, v122, v118
	v_add_f32_e32 v121, v123, v119
	v_cvt_pk_bf16_f32 v188, v118, v119
	v_mfma_f32_32x32x16_bf16 v[2:17], v[114:117], v[190:193], v[2:17]
	v_exp_f32_e32 v114, v112
	v_exp_f32_e32 v115, v113
	v_add_f32_e32 v116, v120, v114
	v_add_f32_e32 v117, v121, v115
	v_cvt_pk_bf16_f32 v189, v114, v115
	v_add_f32_e32 v212, v116, v117
	v_cmp_nge_f32_e32 vcc, s7, v212
	s_cbranch_vccnz .Lrare_u1o

.Lr1u1_LBB0_194:
	s_waitcnt lgkmcnt(2)
	v_mfma_f32_32x32x16_bf16 v[18:33], v[118:121], v[178:181], v[18:33]
	ds_read_b128 v[118:121], v247 offset:57344
	v_exp_f32_e32 v133, v102
	v_exp_f32_e32 v134, v103
	v_add_f32_e32 v131, v131, v133
	v_add_f32_e32 v132, v132, v134
	v_cvt_pk_bf16_f32 v184, v133, v134
	v_mfma_f32_32x32x16_bf16 v[2:17], v[114:117], v[178:181], v[2:17]
	ds_read_b128 v[114:117], v247 offset:61440
	v_exp_f32_e32 v130, v104
	v_exp_f32_e32 v133, v105
	v_add_f32_e32 v131, v131, v130
	v_add_f32_e32 v132, v132, v133
	v_cvt_pk_bf16_f32 v185, v130, v133
	s_waitcnt lgkmcnt(2)
	v_mfma_f32_32x32x16_bf16 v[34:49], v[126:129], v[186:189], v[34:49]
	ds_read_b128 v[202:205], v239 offset:16384
	v_exp_f32_e32 v126, v106
	v_exp_f32_e32 v127, v107
	v_add_f32_e32 v128, v131, v126
	v_add_f32_e32 v129, v132, v127
	v_cvt_pk_bf16_f32 v190, v126, v127
	v_mfma_f32_32x32x16_bf16 v[50:65], v[122:125], v[186:189], v[50:65]
	ds_read_b128 v[194:197], v239 offset:24576
	v_exp_f32_e32 v124, v108
	v_exp_f32_e32 v125, v109
	v_add_f32_e32 v122, v128, v124
	v_add_f32_e32 v123, v129, v125
	v_cvt_pk_bf16_f32 v191, v124, v125
.Lr1u1_LBB0_196:
	s_waitcnt lgkmcnt(2)
	v_mfma_f32_32x32x16_bf16 v[18:33], v[118:121], v[186:189], v[18:33]
	ds_read_b128 v[198:201], v240 offset:16384
	v_exp_f32_e32 v118, v110
	v_exp_f32_e32 v119, v111
	v_add_f32_e32 v120, v122, v118
	v_add_f32_e32 v121, v123, v119
	v_cvt_pk_bf16_f32 v192, v118, v119
	v_mfma_f32_32x32x16_bf16 v[2:17], v[114:117], v[186:189], v[2:17]
	v_exp_f32_e32 v114, v112
	v_exp_f32_e32 v115, v113
	v_add_f32_e32 v116, v120, v114
	v_add_f32_e32 v117, v121, v115
	v_cvt_pk_bf16_f32 v193, v114, v115
	v_add_f32_e32 v212, v116, v117
	v_cmp_nge_f32_e32 vcc, s7, v212
	s_cbranch_vccnz .Lr1u1_Lrare_u1e

.Lr1u1_LBB0_234:
	s_waitcnt lgkmcnt(2)
	v_mfma_f32_32x32x16_bf16 v[18:33], v[118:121], v[182:185], v[18:33]
	ds_read_b128 v[118:121], v247 offset:24576
	v_exp_f32_e32 v135, v102
	v_exp_f32_e32 v136, v103
	v_add_f32_e32 v133, v133, v135
	v_add_f32_e32 v134, v134, v136
	v_cvt_pk_bf16_f32 v180, v135, v136
	v_mfma_f32_32x32x16_bf16 v[2:17], v[114:117], v[182:185], v[2:17]
	ds_read_b128 v[114:117], v247 offset:28672
	v_exp_f32_e32 v132, v104
	v_exp_f32_e32 v135, v105
	v_add_f32_e32 v133, v133, v132
	v_add_f32_e32 v134, v134, v135
	v_cvt_pk_bf16_f32 v181, v132, v135
	s_waitcnt lgkmcnt(2)
	v_mfma_f32_32x32x16_bf16 v[34:49], v[126:129], v[190:193], v[34:49]
	ds_read_b128 v[202:205], v239 offset:32768
	v_exp_f32_e32 v126, v106
	v_exp_f32_e32 v127, v107
	v_add_f32_e32 v128, v133, v126
	v_add_f32_e32 v129, v134, v127
	v_cvt_pk_bf16_f32 v186, v126, v127
	v_mfma_f32_32x32x16_bf16 v[50:65], v[122:125], v[190:193], v[50:65]
	ds_read_b128 v[194:197], v239 offset:40960
	v_exp_f32_e32 v124, v108
	v_exp_f32_e32 v125, v109
	v_add_f32_e32 v122, v128, v124
	v_add_f32_e32 v123, v129, v125
	v_cvt_pk_bf16_f32 v187, v124, v125
.Lr1u1_LBB0_236:
	s_waitcnt lgkmcnt(2)
	v_mfma_f32_32x32x16_bf16 v[18:33], v[118:121], v[190:193], v[18:33]
	ds_read_b128 v[198:201], v240 offset:32768
	v_exp_f32_e32 v118, v110
	v_exp_f32_e32 v119, v111
	v_add_f32_e32 v120, v122, v118
	v_add_f32_e32 v121, v123, v119
	v_cvt_pk_bf16_f32 v188, v118, v119
	v_mfma_f32_32x32x16_bf16 v[2:17], v[114:117], v[190:193], v[2:17]
	v_exp_f32_e32 v114, v112
	v_exp_f32_e32 v115, v113
	v_add_f32_e32 v116, v120, v114
	v_add_f32_e32 v117, v121, v115
	v_cvt_pk_bf16_f32 v189, v114, v115
	v_add_f32_e32 v212, v116, v117
	v_cmp_nge_f32_e32 vcc, s7, v212
	s_cbranch_vccnz .Lr1u1_Lrare_u1o

.Lr2u1_LBB0_194:
	s_waitcnt lgkmcnt(2)
	v_mfma_f32_32x32x16_bf16 v[18:33], v[118:121], v[178:181], v[18:33]
	ds_read_b128 v[118:121], v247 offset:40960
	v_exp_f32_e32 v133, v102
	v_exp_f32_e32 v134, v103
	v_add_f32_e32 v131, v131, v133
	v_add_f32_e32 v132, v132, v134
	v_cvt_pk_bf16_f32 v184, v133, v134
	v_mfma_f32_32x32x16_bf16 v[2:17], v[114:117], v[178:181], v[2:17]
	ds_read_b128 v[114:117], v247 offset:45056
	v_exp_f32_e32 v130, v104
	v_exp_f32_e32 v133, v105
	v_add_f32_e32 v131, v131, v130
	v_add_f32_e32 v132, v132, v133
	v_cvt_pk_bf16_f32 v185, v130, v133
	s_waitcnt lgkmcnt(2)
	v_mfma_f32_32x32x16_bf16 v[34:49], v[126:129], v[186:189], v[34:49]
	ds_read_b128 v[202:205], v239
	v_exp_f32_e32 v126, v106
	v_exp_f32_e32 v127, v107
	v_add_f32_e32 v128, v131, v126
	v_add_f32_e32 v129, v132, v127
	v_cvt_pk_bf16_f32 v190, v126, v127
	v_mfma_f32_32x32x16_bf16 v[50:65], v[122:125], v[186:189], v[50:65]
	ds_read_b128 v[194:197], v239 offset:8192
	v_exp_f32_e32 v124, v108
	v_exp_f32_e32 v125, v109
	v_add_f32_e32 v122, v128, v124
	v_add_f32_e32 v123, v129, v125
	v_cvt_pk_bf16_f32 v191, v124, v125
.Lr2u1_LBB0_196:
	s_waitcnt lgkmcnt(2)
	v_mfma_f32_32x32x16_bf16 v[18:33], v[118:121], v[186:189], v[18:33]
	ds_read_b128 v[198:201], v240
	v_exp_f32_e32 v118, v110
	v_exp_f32_e32 v119, v111
	v_add_f32_e32 v120, v122, v118
	v_add_f32_e32 v121, v123, v119
	v_cvt_pk_bf16_f32 v192, v118, v119
	v_mfma_f32_32x32x16_bf16 v[2:17], v[114:117], v[186:189], v[2:17]
	v_exp_f32_e32 v114, v112
	v_exp_f32_e32 v115, v113
	v_add_f32_e32 v116, v120, v114
	v_add_f32_e32 v117, v121, v115
	v_cvt_pk_bf16_f32 v193, v114, v115
	v_add_f32_e32 v212, v116, v117
	v_cmp_nge_f32_e32 vcc, s7, v212
	s_cbranch_vccnz .Lr2u1_Lrare_u1e

.Lr2u1_LBB0_234:
	s_waitcnt lgkmcnt(2)
	v_mfma_f32_32x32x16_bf16 v[18:33], v[118:121], v[182:185], v[18:33]
	ds_read_b128 v[118:121], v247 offset:57344
	v_exp_f32_e32 v135, v102
	v_exp_f32_e32 v136, v103
	v_add_f32_e32 v133, v133, v135
	v_add_f32_e32 v134, v134, v136
	v_cvt_pk_bf16_f32 v180, v135, v136
	v_mfma_f32_32x32x16_bf16 v[2:17], v[114:117], v[182:185], v[2:17]
	ds_read_b128 v[114:117], v247 offset:61440
	v_exp_f32_e32 v132, v104
	v_exp_f32_e32 v135, v105
	v_add_f32_e32 v133, v133, v132
	v_add_f32_e32 v134, v134, v135
	v_cvt_pk_bf16_f32 v181, v132, v135
	s_waitcnt lgkmcnt(2)
	v_mfma_f32_32x32x16_bf16 v[34:49], v[126:129], v[190:193], v[34:49]
	ds_read_b128 v[202:205], v239 offset:16384
	v_exp_f32_e32 v126, v106
	v_exp_f32_e32 v127, v107
	v_add_f32_e32 v128, v133, v126
	v_add_f32_e32 v129, v134, v127
	v_cvt_pk_bf16_f32 v186, v126, v127
	v_mfma_f32_32x32x16_bf16 v[50:65], v[122:125], v[190:193], v[50:65]
	ds_read_b128 v[194:197], v239 offset:24576
	v_exp_f32_e32 v124, v108
	v_exp_f32_e32 v125, v109
	v_add_f32_e32 v122, v128, v124
	v_add_f32_e32 v123, v129, v125
	v_cvt_pk_bf16_f32 v187, v124, v125
.Lr2u1_LBB0_236:
	s_waitcnt lgkmcnt(2)
	v_mfma_f32_32x32x16_bf16 v[18:33], v[118:121], v[190:193], v[18:33]
	ds_read_b128 v[198:201], v240 offset:16384
	v_exp_f32_e32 v118, v110
	v_exp_f32_e32 v119, v111
	v_add_f32_e32 v120, v122, v118
	v_add_f32_e32 v121, v123, v119
	v_cvt_pk_bf16_f32 v188, v118, v119
	v_mfma_f32_32x32x16_bf16 v[2:17], v[114:117], v[190:193], v[2:17]
	v_exp_f32_e32 v114, v112
	v_exp_f32_e32 v115, v113
	v_add_f32_e32 v116, v120, v114
	v_add_f32_e32 v117, v121, v115
	v_cvt_pk_bf16_f32 v189, v114, v115
	v_add_f32_e32 v212, v116, v117
	v_cmp_nge_f32_e32 vcc, s7, v212
	s_cbranch_vccnz .Lr2u1_Lrare_u1o

.LBB0_297:
	s_waitcnt lgkmcnt(2)
	v_mfma_f32_32x32x16_bf16 v[18:33], v[118:121], v[178:181], v[18:33]
	ds_read_b128 v[118:121], v248 offset:24576
	v_exp_f32_e32 v132, v102
	v_exp_f32_e32 v133, v103
	v_add_f32_e32 v130, v130, v132
	v_add_f32_e32 v131, v131, v133
	v_cvt_pk_bf16_f32 v184, v132, v133
	v_mfma_f32_32x32x16_bf16 v[2:17], v[114:117], v[178:181], v[2:17]
	ds_read_b128 v[114:117], v248 offset:28672
	v_exp_f32_e32 v0, v104
	v_exp_f32_e32 v132, v105
	v_add_f32_e32 v130, v130, v0
	v_add_f32_e32 v131, v131, v132
	v_cvt_pk_bf16_f32 v185, v0, v132
	s_waitcnt lgkmcnt(2)
	v_mfma_f32_32x32x16_bf16 v[50:65], v[126:129], v[186:189], v[50:65]
	ds_read_b128 v[202:205], v239 offset:32768
	v_exp_f32_e32 v0, v106
	v_exp_f32_e32 v126, v107
	v_add_f32_e32 v127, v130, v0
	v_add_f32_e32 v128, v131, v126
	v_cvt_pk_bf16_f32 v190, v0, v126
	v_mfma_f32_32x32x16_bf16 v[34:49], v[122:125], v[186:189], v[34:49]
	ds_read_b128 v[194:197], v239 offset:40960
	v_exp_f32_e32 v123, v108
	v_exp_f32_e32 v124, v109
	v_add_f32_e32 v0, v127, v123
	v_add_f32_e32 v122, v128, v124
	v_cvt_pk_bf16_f32 v191, v123, v124
.LBB0_299:
	s_waitcnt lgkmcnt(2)
	v_mfma_f32_32x32x16_bf16 v[18:33], v[118:121], v[186:189], v[18:33]
	ds_read_b128 v[198:201], v240 offset:32768
	v_exp_f32_e32 v118, v110
	v_exp_f32_e32 v119, v111
	v_add_f32_e32 v0, v0, v118
	v_add_f32_e32 v120, v122, v119
	v_cvt_pk_bf16_f32 v192, v118, v119
	v_mfma_f32_32x32x16_bf16 v[2:17], v[114:117], v[186:189], v[2:17]
	v_exp_f32_e32 v114, v112
	v_exp_f32_e32 v115, v113
	v_add_f32_e32 v0, v0, v114
	v_add_f32_e32 v116, v120, v115
	v_cvt_pk_bf16_f32 v193, v114, v115
	v_add_f32_e32 v212, v0, v116
	v_cmp_nge_f32_e32 vcc, s7, v212
	s_cbranch_vccnz .Lrare_u2e

.LBB0_337:
	s_waitcnt lgkmcnt(2)
	v_mfma_f32_32x32x16_bf16 v[18:33], v[118:121], v[182:185], v[18:33]
	ds_read_b128 v[118:121], v248 offset:40960
	v_exp_f32_e32 v134, v102
	v_exp_f32_e32 v135, v103
	v_add_f32_e32 v132, v132, v134
	v_add_f32_e32 v133, v133, v135
	v_cvt_pk_bf16_f32 v180, v134, v135
	v_mfma_f32_32x32x16_bf16 v[2:17], v[114:117], v[182:185], v[2:17]
	ds_read_b128 v[114:117], v248 offset:45056
	v_exp_f32_e32 v0, v104
	v_exp_f32_e32 v134, v105
	v_add_f32_e32 v132, v132, v0
	v_add_f32_e32 v133, v133, v134
	v_cvt_pk_bf16_f32 v181, v0, v134
	s_waitcnt lgkmcnt(2)
	v_mfma_f32_32x32x16_bf16 v[50:65], v[126:129], v[190:193], v[50:65]
	ds_read_b128 v[202:205], v239
	v_exp_f32_e32 v0, v106
	v_exp_f32_e32 v126, v107
	v_add_f32_e32 v127, v132, v0
	v_add_f32_e32 v128, v133, v126
	v_cvt_pk_bf16_f32 v186, v0, v126
	v_mfma_f32_32x32x16_bf16 v[34:49], v[122:125], v[190:193], v[34:49]
	ds_read_b128 v[194:197], v239 offset:8192
	v_exp_f32_e32 v123, v108
	v_exp_f32_e32 v124, v109
	v_add_f32_e32 v0, v127, v123
	v_add_f32_e32 v122, v128, v124
	v_cvt_pk_bf16_f32 v187, v123, v124
.LBB0_339:
	s_waitcnt lgkmcnt(2)
	v_mfma_f32_32x32x16_bf16 v[18:33], v[118:121], v[190:193], v[18:33]
	ds_read_b128 v[198:201], v240
	v_exp_f32_e32 v118, v110
	v_exp_f32_e32 v119, v111
	v_add_f32_e32 v0, v0, v118
	v_add_f32_e32 v120, v122, v119
	v_cvt_pk_bf16_f32 v188, v118, v119
	v_mfma_f32_32x32x16_bf16 v[2:17], v[114:117], v[190:193], v[2:17]
	v_exp_f32_e32 v114, v112
	v_exp_f32_e32 v115, v113
	v_add_f32_e32 v0, v0, v114
	v_add_f32_e32 v116, v120, v115
	v_cvt_pk_bf16_f32 v189, v114, v115
	v_add_f32_e32 v212, v0, v116
	v_cmp_nge_f32_e32 vcc, s7, v212
	s_cbranch_vccnz .Lrare_u2o

.Lr1u2_LBB0_297:
	s_waitcnt lgkmcnt(2)
	v_mfma_f32_32x32x16_bf16 v[18:33], v[118:121], v[178:181], v[18:33]
	ds_read_b128 v[118:121], v248 offset:57344
	v_exp_f32_e32 v132, v102
	v_exp_f32_e32 v133, v103
	v_add_f32_e32 v130, v130, v132
	v_add_f32_e32 v131, v131, v133
	v_cvt_pk_bf16_f32 v184, v132, v133
	v_mfma_f32_32x32x16_bf16 v[2:17], v[114:117], v[178:181], v[2:17]
	ds_read_b128 v[114:117], v248 offset:61440
	v_exp_f32_e32 v0, v104
	v_exp_f32_e32 v132, v105
	v_add_f32_e32 v130, v130, v0
	v_add_f32_e32 v131, v131, v132
	v_cvt_pk_bf16_f32 v185, v0, v132
	s_waitcnt lgkmcnt(2)
	v_mfma_f32_32x32x16_bf16 v[50:65], v[126:129], v[186:189], v[50:65]
	ds_read_b128 v[202:205], v239 offset:16384
	v_exp_f32_e32 v0, v106
	v_exp_f32_e32 v126, v107
	v_add_f32_e32 v127, v130, v0
	v_add_f32_e32 v128, v131, v126
	v_cvt_pk_bf16_f32 v190, v0, v126
	v_mfma_f32_32x32x16_bf16 v[34:49], v[122:125], v[186:189], v[34:49]
	ds_read_b128 v[194:197], v239 offset:24576
	v_exp_f32_e32 v123, v108
	v_exp_f32_e32 v124, v109
	v_add_f32_e32 v0, v127, v123
	v_add_f32_e32 v122, v128, v124
	v_cvt_pk_bf16_f32 v191, v123, v124
.Lr1u2_LBB0_299:
	s_waitcnt lgkmcnt(2)
	v_mfma_f32_32x32x16_bf16 v[18:33], v[118:121], v[186:189], v[18:33]
	ds_read_b128 v[198:201], v240 offset:16384
	v_exp_f32_e32 v118, v110
	v_exp_f32_e32 v119, v111
	v_add_f32_e32 v0, v0, v118
	v_add_f32_e32 v120, v122, v119
	v_cvt_pk_bf16_f32 v192, v118, v119
	v_mfma_f32_32x32x16_bf16 v[2:17], v[114:117], v[186:189], v[2:17]
	v_exp_f32_e32 v114, v112
	v_exp_f32_e32 v115, v113
	v_add_f32_e32 v0, v0, v114
	v_add_f32_e32 v116, v120, v115
	v_cvt_pk_bf16_f32 v193, v114, v115
	v_add_f32_e32 v212, v0, v116
	v_cmp_nge_f32_e32 vcc, s7, v212
	s_cbranch_vccnz .Lr1u2_Lrare_u2e

.Lr1u2_LBB0_337:
	s_waitcnt lgkmcnt(2)
	v_mfma_f32_32x32x16_bf16 v[18:33], v[118:121], v[182:185], v[18:33]
	ds_read_b128 v[118:121], v248 offset:24576
	v_exp_f32_e32 v134, v102
	v_exp_f32_e32 v135, v103
	v_add_f32_e32 v132, v132, v134
	v_add_f32_e32 v133, v133, v135
	v_cvt_pk_bf16_f32 v180, v134, v135
	v_mfma_f32_32x32x16_bf16 v[2:17], v[114:117], v[182:185], v[2:17]
	ds_read_b128 v[114:117], v248 offset:28672
	v_exp_f32_e32 v0, v104
	v_exp_f32_e32 v134, v105
	v_add_f32_e32 v132, v132, v0
	v_add_f32_e32 v133, v133, v134
	v_cvt_pk_bf16_f32 v181, v0, v134
	s_waitcnt lgkmcnt(2)
	v_mfma_f32_32x32x16_bf16 v[50:65], v[126:129], v[190:193], v[50:65]
	ds_read_b128 v[202:205], v239 offset:32768
	v_exp_f32_e32 v0, v106
	v_exp_f32_e32 v126, v107
	v_add_f32_e32 v127, v132, v0
	v_add_f32_e32 v128, v133, v126
	v_cvt_pk_bf16_f32 v186, v0, v126
	v_mfma_f32_32x32x16_bf16 v[34:49], v[122:125], v[190:193], v[34:49]
	ds_read_b128 v[194:197], v239 offset:40960
	v_exp_f32_e32 v123, v108
	v_exp_f32_e32 v124, v109
	v_add_f32_e32 v0, v127, v123
	v_add_f32_e32 v122, v128, v124
	v_cvt_pk_bf16_f32 v187, v123, v124
.Lr1u2_LBB0_339:
	s_waitcnt lgkmcnt(2)
	v_mfma_f32_32x32x16_bf16 v[18:33], v[118:121], v[190:193], v[18:33]
	ds_read_b128 v[198:201], v240 offset:32768
	v_exp_f32_e32 v118, v110
	v_exp_f32_e32 v119, v111
	v_add_f32_e32 v0, v0, v118
	v_add_f32_e32 v120, v122, v119
	v_cvt_pk_bf16_f32 v188, v118, v119
	v_mfma_f32_32x32x16_bf16 v[2:17], v[114:117], v[190:193], v[2:17]
	v_exp_f32_e32 v114, v112
	v_exp_f32_e32 v115, v113
	v_add_f32_e32 v0, v0, v114
	v_add_f32_e32 v116, v120, v115
	v_cvt_pk_bf16_f32 v189, v114, v115
	v_add_f32_e32 v212, v0, v116
	v_cmp_nge_f32_e32 vcc, s7, v212
	s_cbranch_vccnz .Lr1u2_Lrare_u2o

.Lr2u2_LBB0_297:
	s_waitcnt lgkmcnt(2)
	v_mfma_f32_32x32x16_bf16 v[18:33], v[118:121], v[178:181], v[18:33]
	ds_read_b128 v[118:121], v248 offset:40960
	v_exp_f32_e32 v132, v102
	v_exp_f32_e32 v133, v103
	v_add_f32_e32 v130, v130, v132
	v_add_f32_e32 v131, v131, v133
	v_cvt_pk_bf16_f32 v184, v132, v133
	v_mfma_f32_32x32x16_bf16 v[2:17], v[114:117], v[178:181], v[2:17]
	ds_read_b128 v[114:117], v248 offset:45056
	v_exp_f32_e32 v0, v104
	v_exp_f32_e32 v132, v105
	v_add_f32_e32 v130, v130, v0
	v_add_f32_e32 v131, v131, v132
	v_cvt_pk_bf16_f32 v185, v0, v132
	s_waitcnt lgkmcnt(2)
	v_mfma_f32_32x32x16_bf16 v[50:65], v[126:129], v[186:189], v[50:65]
	ds_read_b128 v[202:205], v239
	v_exp_f32_e32 v0, v106
	v_exp_f32_e32 v126, v107
	v_add_f32_e32 v127, v130, v0
	v_add_f32_e32 v128, v131, v126
	v_cvt_pk_bf16_f32 v190, v0, v126
	v_mfma_f32_32x32x16_bf16 v[34:49], v[122:125], v[186:189], v[34:49]
	ds_read_b128 v[194:197], v239 offset:8192
	v_exp_f32_e32 v123, v108
	v_exp_f32_e32 v124, v109
	v_add_f32_e32 v0, v127, v123
	v_add_f32_e32 v122, v128, v124
	v_cvt_pk_bf16_f32 v191, v123, v124
.Lr2u2_LBB0_299:
	s_waitcnt lgkmcnt(2)
	v_mfma_f32_32x32x16_bf16 v[18:33], v[118:121], v[186:189], v[18:33]
	ds_read_b128 v[198:201], v240
	v_exp_f32_e32 v118, v110
	v_exp_f32_e32 v119, v111
	v_add_f32_e32 v0, v0, v118
	v_add_f32_e32 v120, v122, v119
	v_cvt_pk_bf16_f32 v192, v118, v119
	v_mfma_f32_32x32x16_bf16 v[2:17], v[114:117], v[186:189], v[2:17]
	v_exp_f32_e32 v114, v112
	v_exp_f32_e32 v115, v113
	v_add_f32_e32 v0, v0, v114
	v_add_f32_e32 v116, v120, v115
	v_cvt_pk_bf16_f32 v193, v114, v115
	v_add_f32_e32 v212, v0, v116
	v_cmp_nge_f32_e32 vcc, s7, v212
	s_cbranch_vccnz .Lr2u2_Lrare_u2e

.Lr2u2_LBB0_337:
	s_waitcnt lgkmcnt(2)
	v_mfma_f32_32x32x16_bf16 v[18:33], v[118:121], v[182:185], v[18:33]
	ds_read_b128 v[118:121], v248 offset:57344
	v_exp_f32_e32 v134, v102
	v_exp_f32_e32 v135, v103
	v_add_f32_e32 v132, v132, v134
	v_add_f32_e32 v133, v133, v135
	v_cvt_pk_bf16_f32 v180, v134, v135
	v_mfma_f32_32x32x16_bf16 v[2:17], v[114:117], v[182:185], v[2:17]
	ds_read_b128 v[114:117], v248 offset:61440
	v_exp_f32_e32 v0, v104
	v_exp_f32_e32 v134, v105
	v_add_f32_e32 v132, v132, v0
	v_add_f32_e32 v133, v133, v134
	v_cvt_pk_bf16_f32 v181, v0, v134
	s_waitcnt lgkmcnt(2)
	v_mfma_f32_32x32x16_bf16 v[50:65], v[126:129], v[190:193], v[50:65]
	ds_read_b128 v[202:205], v239 offset:16384
	v_exp_f32_e32 v0, v106
	v_exp_f32_e32 v126, v107
	v_add_f32_e32 v127, v132, v0
	v_add_f32_e32 v128, v133, v126
	v_cvt_pk_bf16_f32 v186, v0, v126
	v_mfma_f32_32x32x16_bf16 v[34:49], v[122:125], v[190:193], v[34:49]
	ds_read_b128 v[194:197], v239 offset:24576
	v_exp_f32_e32 v123, v108
	v_exp_f32_e32 v124, v109
	v_add_f32_e32 v0, v127, v123
	v_add_f32_e32 v122, v128, v124
	v_cvt_pk_bf16_f32 v187, v123, v124
.Lr2u2_LBB0_339:
	s_waitcnt lgkmcnt(2)
	v_mfma_f32_32x32x16_bf16 v[18:33], v[118:121], v[190:193], v[18:33]
	ds_read_b128 v[198:201], v240 offset:16384
	v_exp_f32_e32 v118, v110
	v_exp_f32_e32 v119, v111
	v_add_f32_e32 v0, v0, v118
	v_add_f32_e32 v120, v122, v119
	v_cvt_pk_bf16_f32 v188, v118, v119
	v_mfma_f32_32x32x16_bf16 v[2:17], v[114:117], v[190:193], v[2:17]
	v_exp_f32_e32 v114, v112
	v_exp_f32_e32 v115, v113
	v_add_f32_e32 v0, v0, v114
	v_add_f32_e32 v116, v120, v115
	v_cvt_pk_bf16_f32 v189, v114, v115
	v_add_f32_e32 v212, v0, v116
	v_cmp_nge_f32_e32 vcc, s7, v212
	s_cbranch_vccnz .Lr2u2_Lrare_u2o
